# attention K/V tile staging via LDS-DMA (global_load_lds) in diff + NSA sel/win loops, on top of GEMM setprio + VALU trims
# speedup vs baseline: 1.0085x; 1.0085x over previous
.LBB0_44:
	s_cmpk_gt_i32 s54, 0x7ff
	s_cbranch_scc1 .LBB0_43
	s_waitcnt vmcnt(10)
	v_mov_b32_e32 v54, v224
	s_ashr_i32 s55, s54, 5
	v_readfirstlane_b32 s0, v54
	s_sub_i32 s57, 63, s55
	s_ashr_i32 s0, s0, 1
	s_lshl_b32 s1, s57, 7
	s_and_b32 s52, s0, 0xffffffe0
	s_add_i32 s52, s52, s1
	s_bfe_u32 s56, s54, 0x10004
	s_and_b32 s48, s54, 15
	v_and_or_b32 v170, v54, 15, s52
	s_lshl_b32 s94, s56, 13
	s_lshl_b32 s0, s48, 7
	v_ashrrev_i32_e32 v171, 31, v170
	s_add_u32 s0, s13, s0
	v_lshl_add_u64 v[172:173], v[170:171], 0, s[94:95]
	s_addc_u32 s1, s14, 0
	v_and_b32_e32 v0, 16, v54
	v_lshlrev_b64 v[2:3], 11, v[172:173]
	v_cmp_eq_u32_e64 s[40:41], 0, v0
	s_waitcnt vmcnt(1)
	v_lshl_add_u64 v[14:15], s[0:1], 0, v[2:3]
	v_and_b32_e32 v0, 48, v54
	v_lshl_add_u64 v[6:7], v[14:15], 0, v[0:1]
	v_lshlrev_b64 v[10:11], 6, v[170:171]
	global_load_dwordx4 v[2:5], v[6:7], off offset:64
	s_nop 0
	global_load_dwordx4 v[6:9], v[6:7], off
	v_lshl_add_u64 v[22:23], s[4:5], 0, v[10:11]
	global_load_dwordx4 v[10:13], v[14:15], off
	s_nop 0
	global_load_dwordx4 v[14:17], v[14:15], off offset:16
	v_or_b32_e32 v176, 16, v170
	v_and_b32_e32 v55, 63, v54
	v_ashrrev_i32_e32 v177, 31, v176
	v_cmp_gt_u32_e32 vcc, 32, v55
	v_lshl_add_u64 v[174:175], v[176:177], 0, s[94:95]
	v_mov_b32_e32 v90, v1
	v_mov_b32_e32 v91, v1
	v_mov_b32_e32 v92, v1
	v_mov_b32_e32 v93, v1
	v_lshlrev_b32_e32 v193, 4, v54
	v_lshlrev_b32_e32 v197, 4, v55
	v_mov_b64_e32 v[70:71], v[90:91]
	v_mov_b64_e32 v[104:105], v[92:93]
	v_mov_b64_e32 v[66:67], v[90:91]
	v_mov_b64_e32 v[100:101], v[92:93]
	v_mov_b64_e32 v[58:59], v[90:91]
	v_mov_b64_e32 v[96:97], v[92:93]
	v_mov_b64_e32 v[86:87], v[90:91]
	v_mov_b64_e32 v[82:83], v[90:91]
	v_mov_b64_e32 v[78:79], v[90:91]
	v_mov_b64_e32 v[74:75], v[90:91]
	s_mov_b32 s49, 63
	s_mov_b32 s53, 0
	v_mov_b32_e32 v200, 0xf149f2ca
	v_mov_b32_e32 v198, 0xf149f2ca
	v_mov_b64_e32 v[72:73], v[92:93]
	v_mov_b64_e32 v[102:103], v[90:91]
	v_mov_b64_e32 v[68:69], v[92:93]
	v_mov_b64_e32 v[98:99], v[90:91]
	v_mov_b64_e32 v[60:61], v[92:93]
	v_mov_b64_e32 v[94:95], v[90:91]
	v_mov_b64_e32 v[88:89], v[92:93]
	v_mov_b64_e32 v[84:85], v[92:93]
	v_mov_b64_e32 v[80:81], v[92:93]
	v_mov_b64_e32 v[76:77], v[92:93]
	s_waitcnt vmcnt(1)
	v_lshlrev_b32_e32 v26, 16, v10
	s_waitcnt vmcnt(0)
	v_lshlrev_b32_e32 v27, 16, v14
	v_and_b32_e32 v29, 0xffff0000, v14
	v_and_b32_e32 v28, 0xffff0000, v10
	v_lshlrev_b32_e32 v31, 16, v15
	v_lshlrev_b32_e32 v30, 16, v11
	v_and_b32_e32 v33, 0xffff0000, v15
	v_and_b32_e32 v32, 0xffff0000, v11
	v_lshlrev_b32_e32 v35, 16, v16
	v_lshlrev_b32_e32 v34, 16, v12
	v_and_b32_e32 v37, 0xffff0000, v16
	v_and_b32_e32 v36, 0xffff0000, v12
	v_lshlrev_b32_e32 v39, 16, v17
	v_lshlrev_b32_e32 v38, 16, v13
	v_and_b32_e32 v41, 0xffff0000, v17
	v_and_b32_e32 v40, 0xffff0000, v13
	global_load_dwordx4 v[10:13], v[22:23], off offset:48
	global_load_dwordx4 v[14:17], v[22:23], off offset:16
	global_load_dwordx4 v[18:21], v[22:23], off offset:32
	s_nop 0
	global_load_dwordx4 v[22:25], v[22:23], off
	s_waitcnt vmcnt(1)
	v_mov_b32_e32 v43, v18
	s_waitcnt vmcnt(0)
	v_mov_b32_e32 v42, v22
	v_pk_mul_f32 v[42:43], v[42:43], v[26:27]
	s_nop 0
	v_sub_f32_e32 v44, v42, v43
	v_mov_b32_e32 v42, v18
	v_mov_b32_e32 v43, v22
	v_pk_mul_f32 v[26:27], v[42:43], v[26:27]
	v_mov_b32_e32 v22, v19
	v_add_f32_e32 v18, v26, v27
	v_cndmask_b32_e64 v42, v18, v44, s[40:41]
	v_mov_b32_e32 v18, v23
	v_pk_mul_f32 v[26:27], v[18:19], v[28:29]
	v_pk_mul_f32 v[18:19], v[22:23], v[28:29]
	v_sub_f32_e32 v26, v26, v27
	v_add_f32_e32 v18, v19, v18
	v_cndmask_b32_e64 v22, v18, v26, s[40:41]
	v_mov_b32_e32 v18, v24
	v_mov_b32_e32 v19, v20
	v_pk_mul_f32 v[18:19], v[18:19], v[30:31]
	s_nop 0
	v_sub_f32_e32 v23, v18, v19
	v_mov_b32_e32 v18, v20
	v_mov_b32_e32 v19, v24
	v_pk_mul_f32 v[18:19], v[18:19], v[30:31]
	v_mov_b32_e32 v20, v25
	v_add_f32_e32 v18, v19, v18
	v_cndmask_b32_e64 v23, v18, v23, s[40:41]
	v_pk_mul_f32 v[18:19], v[20:21], v[32:33]
	v_mov_b32_e32 v24, v21
	v_sub_f32_e32 v20, v18, v19
	v_pk_mul_f32 v[18:19], v[24:25], v[32:33]
	s_nop 0
	v_add_f32_e32 v18, v19, v18
	v_cndmask_b32_e64 v20, v18, v20, s[40:41]
	v_mov_b32_e32 v18, v14
	v_mov_b32_e32 v19, v10
	v_pk_mul_f32 v[18:19], v[18:19], v[34:35]
	s_nop 0
	v_sub_f32_e32 v21, v18, v19
	v_mov_b32_e32 v18, v10
	v_mov_b32_e32 v19, v14
	v_pk_mul_f32 v[18:19], v[18:19], v[34:35]
	v_mov_b32_e32 v14, v11
	v_add_f32_e32 v10, v19, v18
	v_cndmask_b32_e64 v21, v10, v21, s[40:41]
	v_mov_b32_e32 v10, v15
	v_pk_mul_f32 v[18:19], v[10:11], v[36:37]
	v_pk_mul_f32 v[10:11], v[14:15], v[36:37]
	v_sub_f32_e32 v18, v18, v19
	v_add_f32_e32 v10, v11, v10
	v_cndmask_b32_e64 v14, v10, v18, s[40:41]
	v_mov_b32_e32 v10, v16
	v_mov_b32_e32 v11, v12
	v_pk_mul_f32 v[10:11], v[10:11], v[38:39]
	v_lshlrev_b64 v[18:19], 6, v[176:177]
	v_sub_f32_e32 v15, v10, v11
	v_mov_b32_e32 v10, v12
	v_mov_b32_e32 v11, v16
	v_pk_mul_f32 v[10:11], v[10:11], v[38:39]
	v_mov_b32_e32 v12, v17
	v_add_f32_e32 v10, v11, v10
	v_cndmask_b32_e64 v15, v10, v15, s[40:41]
	v_pk_mul_f32 v[10:11], v[12:13], v[40:41]
	v_mov_b32_e32 v16, v13
	v_sub_f32_e32 v12, v10, v11
	v_pk_mul_f32 v[10:11], v[16:17], v[40:41]
	v_cvt_pk_bf16_f32 v13, v21, v14
	v_add_f32_e32 v10, v11, v10
	v_cndmask_b32_e64 v10, v10, v12, s[40:41]
	v_cvt_pk_bf16_f32 v11, v42, v22
	v_cvt_pk_bf16_f32 v10, v15, v10
	v_cndmask_b32_e32 v9, v9, v10, vcc
	v_cndmask_b32_e32 v6, v6, v11, vcc
	v_lshlrev_b64 v[10:11], 11, v[174:175]
	v_cvt_pk_bf16_f32 v12, v23, v20
	v_lshl_add_u64 v[22:23], s[0:1], 0, v[10:11]
	v_lshl_add_u64 v[14:15], v[22:23], 0, v[0:1]
	v_cndmask_b32_e32 v8, v8, v13, vcc
	v_cndmask_b32_e32 v7, v7, v12, vcc
	global_load_dwordx4 v[10:13], v[14:15], off offset:64
	s_nop 0
	global_load_dwordx4 v[14:17], v[14:15], off
	v_lshl_add_u64 v[30:31], s[4:5], 0, v[18:19]
	global_load_dwordx4 v[18:21], v[22:23], off
	s_nop 0
	global_load_dwordx4 v[22:25], v[22:23], off offset:16
	s_waitcnt vmcnt(1)
	v_lshlrev_b32_e32 v48, 16, v18
	s_waitcnt vmcnt(0)
	v_lshlrev_b32_e32 v49, 16, v22
	v_and_b32_e32 v47, 0xffff0000, v22
	v_and_b32_e32 v46, 0xffff0000, v18
	v_lshlrev_b32_e32 v45, 16, v23
	v_lshlrev_b32_e32 v44, 16, v19
	v_and_b32_e32 v43, 0xffff0000, v23
	v_and_b32_e32 v42, 0xffff0000, v19
	v_lshlrev_b32_e32 v41, 16, v24
	v_lshlrev_b32_e32 v40, 16, v20
	v_and_b32_e32 v39, 0xffff0000, v24
	v_and_b32_e32 v38, 0xffff0000, v20
	v_lshlrev_b32_e32 v37, 16, v25
	v_lshlrev_b32_e32 v36, 16, v21
	v_and_b32_e32 v35, 0xffff0000, v25
	v_and_b32_e32 v34, 0xffff0000, v21
	global_load_dwordx4 v[18:21], v[30:31], off offset:48
	global_load_dwordx4 v[22:25], v[30:31], off offset:16
	global_load_dwordx4 v[26:29], v[30:31], off offset:32
	s_nop 0
	global_load_dwordx4 v[30:33], v[30:31], off
	s_barrier
	s_waitcnt vmcnt(1)
	v_mov_b32_e32 v51, v26
	s_waitcnt vmcnt(0)
	v_mov_b32_e32 v50, v30
	v_pk_mul_f32 v[50:51], v[50:51], v[48:49]
	s_nop 0
	v_sub_f32_e32 v0, v50, v51
	v_mov_b32_e32 v50, v26
	v_mov_b32_e32 v51, v30
	v_pk_mul_f32 v[48:49], v[50:51], v[48:49]
	v_mov_b32_e32 v30, v27
	v_add_f32_e32 v26, v48, v49
	v_cndmask_b32_e64 v0, v26, v0, s[40:41]
	v_mov_b32_e32 v26, v31
	v_pk_mul_f32 v[48:49], v[26:27], v[46:47]
	v_pk_mul_f32 v[26:27], v[30:31], v[46:47]
	v_sub_f32_e32 v48, v48, v49
	v_add_f32_e32 v26, v27, v26
	v_cndmask_b32_e64 v30, v26, v48, s[40:41]
	v_mov_b32_e32 v26, v32
	v_mov_b32_e32 v27, v28
	v_pk_mul_f32 v[26:27], v[26:27], v[44:45]
	v_cvt_pk_bf16_f32 v0, v0, v30
	v_sub_f32_e32 v31, v26, v27
	v_mov_b32_e32 v26, v28
	v_mov_b32_e32 v27, v32
	v_pk_mul_f32 v[26:27], v[26:27], v[44:45]
	v_mov_b32_e32 v28, v33
	v_add_f32_e32 v26, v27, v26
	v_cndmask_b32_e64 v31, v26, v31, s[40:41]
	v_pk_mul_f32 v[26:27], v[28:29], v[42:43]
	v_mov_b32_e32 v32, v29
	v_sub_f32_e32 v28, v26, v27
	v_pk_mul_f32 v[26:27], v[32:33], v[42:43]
	v_cndmask_b32_e32 v14, v14, v0, vcc
	v_add_f32_e32 v26, v27, v26
	v_cndmask_b32_e64 v28, v26, v28, s[40:41]
	v_mov_b32_e32 v26, v22
	v_mov_b32_e32 v27, v18
	v_pk_mul_f32 v[26:27], v[26:27], v[40:41]
	v_mov_b64_e32 v[46:47], v[90:91]
	v_sub_f32_e32 v29, v26, v27
	v_mov_b32_e32 v26, v18
	v_mov_b32_e32 v27, v22
	v_pk_mul_f32 v[26:27], v[26:27], v[40:41]
	v_mov_b32_e32 v22, v19
	v_add_f32_e32 v18, v27, v26
	v_cndmask_b32_e64 v29, v18, v29, s[40:41]
	v_mov_b32_e32 v18, v23
	v_pk_mul_f32 v[26:27], v[18:19], v[38:39]
	v_pk_mul_f32 v[18:19], v[22:23], v[38:39]
	v_sub_f32_e32 v26, v26, v27
	v_add_f32_e32 v18, v19, v18
	v_cndmask_b32_e64 v22, v18, v26, s[40:41]
	v_mov_b32_e32 v18, v24
	v_mov_b32_e32 v19, v20
	v_pk_mul_f32 v[18:19], v[18:19], v[36:37]
	v_lshlrev_b32_e32 v26, 3, v54
	v_sub_f32_e32 v23, v18, v19
	v_mov_b32_e32 v18, v20
	v_mov_b32_e32 v19, v24
	v_pk_mul_f32 v[18:19], v[18:19], v[36:37]
	v_mov_b32_e32 v20, v25
	v_add_f32_e32 v18, v19, v18
	v_cndmask_b32_e64 v23, v18, v23, s[40:41]
	v_pk_mul_f32 v[18:19], v[20:21], v[34:35]
	v_mov_b32_e32 v24, v21
	v_sub_f32_e32 v20, v18, v19
	v_pk_mul_f32 v[18:19], v[24:25], v[34:35]
	v_ashrrev_i32_e32 v27, 31, v26
	v_add_f32_e32 v18, v19, v18
	v_cndmask_b32_e64 v18, v18, v20, s[40:41]
	s_lshl_b32 s40, s54, 20
	v_cvt_pk_bf16_f32 v20, v29, v22
	s_and_b32 s0, s40, 0x1f00000
	v_add_u32_e32 v22, 0x800, v26
	v_cvt_pk_bf16_f32 v18, v23, v18
	s_add_u32 s0, s15, s0
	v_ashrrev_i32_e32 v23, 31, v22
	v_cvt_pk_bf16_f32 v19, v31, v28
	s_addc_u32 s1, s44, 0
	v_lshlrev_b64 v[28:29], 1, v[26:27]
	v_lshlrev_b64 v[34:35], 1, v[22:23]
	v_cndmask_b32_e32 v17, v17, v18, vcc
	v_cndmask_b32_e32 v15, v15, v19, vcc
	v_lshl_add_u64 v[18:19], s[0:1], 0, v[28:29]
	v_lshl_add_u64 v[22:23], s[0:1], 0, v[34:35]
	s_and_b32 s0, s40, 0xe00000
	s_lshl_b32 s1, s56, 24
	s_lshl_b32 s41, s57, 1
	s_or_b32 s40, s1, s0
	s_add_u32 s0, s45, s40
	s_addc_u32 s1, s46, 0
	v_lshl_add_u64 v[30:31], s[0:1], 0, v[28:29]
	v_lshl_add_u64 v[36:37], s[0:1], 0, v[34:35]
	global_load_dwordx4 v[30:33], v[30:31], off
	v_cndmask_b32_e32 v16, v16, v20, vcc
	global_load_dwordx4 v[42:45], v[36:37], off
	v_add_u32_e32 v36, 0x1000, v26
	v_ashrrev_i32_e32 v37, 31, v36
	v_add_u32_e32 v26, 0x1800, v26
	v_lshlrev_b64 v[36:37], 1, v[36:37]
	v_ashrrev_i32_e32 v27, 31, v26
	v_lshl_add_u64 v[38:39], s[0:1], 0, v[36:37]
	v_lshlrev_b64 v[26:27], 1, v[26:27]
	global_load_dwordx4 v[50:53], v[38:39], off
	v_lshl_add_u64 v[38:39], s[0:1], 0, v[26:27]
	global_load_dwordx4 v[18:21], v[18:19], off
	s_add_i32 s0, s41, 2
	global_load_dwordx4 v[22:25], v[22:23], off
	v_readlane_b32 s1, v254, 13
	global_load_dwordx4 v[62:65], v[38:39], off
	s_add_u32 s40, s1, s40
	v_readlane_b32 s1, v254, 14
	v_cmp_lt_i32_e32 vcc, v247, v214
	s_addc_u32 s41, s1, 0
	s_and_b32 s1, s54, 31
	v_cndmask_b32_e32 v0, v225, v247, vcc
	v_cmp_lt_i32_e32 vcc, v246, v214
	v_mov_b32_e32 v180, v34
	v_mov_b32_e32 v181, v28
	v_mov_b32_e32 v182, v36
	s_mov_b64 s[98:99], s[40:41]
	v_mov_b32_e32 v184, v26
	s_lshl_b32 s1, s1, 20
	v_readlane_b32 s40, v254, 15
	v_lshlrev_b32_e32 v177, 2, v0
	v_cndmask_b32_e32 v0, v225, v246, vcc
	s_add_u32 s40, s40, s1
	v_readlane_b32 s1, v254, 16
	v_lshlrev_b32_e32 v171, 2, v0
	v_lshrrev_b32_e32 v0, 2, v54
	s_addc_u32 s41, s1, 0
	v_and_b32_e32 v192, 12, v0
	s_mov_b64 s[2:3], s[40:41]
	s_lshl_b32 s1, s55, 1
	v_mov_b32_e32 v0, v1
	v_mov_b64_e32 v[54:55], v[90:91]
	v_mov_b64_e32 v[38:39], v[90:91]
	v_mov_b64_e32 v[34:35], v[90:91]
	v_mov_b64_e32 v[26:27], v[90:91]
	s_sub_i32 s1, 0, s1
	s_movk_i32 s54, 0xff80
	v_mov_b64_e32 v[56:57], v[92:93]
	v_mov_b64_e32 v[48:49], v[92:93]
	v_mov_b64_e32 v[40:41], v[92:93]
	v_mov_b64_e32 v[36:37], v[92:93]
	v_mov_b64_e32 v[28:29], v[92:93]
	v_mov_b64_e32 v[178:179], v[0:1]
	s_waitcnt vmcnt(0)
	ds_write_b128 v193, v[18:21]
	ds_write_b128 v193, v[22:25] offset:4096
	ds_write_b128 v193, v[30:33] offset:8192
	ds_write_b128 v193, v[42:45] offset:12288
	ds_write_b128 v193, v[50:53] offset:16384
	ds_write_b128 v193, v[62:65] offset:20480
.LBB0_46:
	s_mul_i32 s40, s53, 0x6000
	s_add_i32 s41, s54, 0x81
	s_cmp_ge_u32 s41, s0
	s_waitcnt vmcnt(0)
	s_waitcnt lgkmcnt(0)
	s_barrier
	s_cbranch_scc1 .LBB0_48
	v_readfirstlane_b32 s41, v193
	s_sub_u32 m0, 0x6000, s40
	s_nop 0
	s_add_u32 m0, m0, s41
	s_nop 0
	global_load_lds_dwordx4 v181, s[2:3]
	s_add_u32 m0, m0, 0x1000
	s_nop 0
	global_load_lds_dwordx4 v180, s[2:3]
	s_add_u32 m0, m0, 0x1000
	s_nop 0
	global_load_lds_dwordx4 v181, s[98:99]
	s_add_u32 m0, m0, 0x1000
	s_nop 0
	global_load_lds_dwordx4 v180, s[98:99]
	s_add_u32 m0, m0, 0x1000
	s_nop 0
	global_load_lds_dwordx4 v182, s[98:99]
	s_add_u32 m0, m0, 0x1000
	s_nop 0
	global_load_lds_dwordx4 v184, s[98:99]

.LBB0_394:
	v_lshlrev_b32_e32 v9, 16, v82
	v_lshlrev_b32_e32 v8, 16, v86
	v_mov_b32_e32 v24, v78
	v_mov_b32_e32 v25, v74
	v_pk_mul_f32 v[24:25], v[24:25], v[8:9]
	v_and_b32_e32 v11, 0xffff0000, v82
	v_sub_f32_e32 v0, v24, v25
	v_mov_b32_e32 v24, v74
	v_mov_b32_e32 v25, v78
	v_and_b32_e32 v10, 0xffff0000, v86
	v_pk_mul_f32 v[8:9], v[24:25], v[8:9]
	v_mov_b32_e32 v74, v79
	v_add_f32_e32 v5, v8, v9
	v_cmp_gt_u32_e32 vcc, 32, v185
	v_pk_mul_f32 v[8:9], v[74:75], v[10:11]
	v_mov_b32_e32 v78, v75
	v_cndmask_b32_e32 v0, v5, v0, vcc
	v_sub_f32_e32 v5, v8, v9
	v_pk_mul_f32 v[8:9], v[78:79], v[10:11]
	v_lshlrev_b32_e32 v13, 16, v83
	v_lshlrev_b32_e32 v12, 16, v87
	v_add_f32_e32 v7, v9, v8
	v_mov_b32_e32 v8, v80
	v_mov_b32_e32 v9, v76
	v_pk_mul_f32 v[8:9], v[8:9], v[12:13]
	v_cndmask_b32_e32 v5, v7, v5, vcc
	v_sub_f32_e32 v7, v8, v9
	v_mov_b32_e32 v8, v76
	v_mov_b32_e32 v9, v80
	v_pk_mul_f32 v[8:9], v[8:9], v[12:13]
	v_and_b32_e32 v15, 0xffff0000, v83
	v_and_b32_e32 v14, 0xffff0000, v87
	v_add_f32_e32 v8, v9, v8
	v_mov_b32_e32 v76, v81
	v_cndmask_b32_e32 v7, v8, v7, vcc
	v_pk_mul_f32 v[8:9], v[76:77], v[14:15]
	v_mov_b32_e32 v80, v77
	v_sub_f32_e32 v10, v8, v9
	v_pk_mul_f32 v[8:9], v[80:81], v[14:15]
	v_lshlrev_b32_e32 v17, 16, v84
	v_add_f32_e32 v8, v9, v8
	v_lshlrev_b32_e32 v16, 16, v88
	v_cndmask_b32_e32 v10, v8, v10, vcc
	v_mov_b32_e32 v8, v70
	v_mov_b32_e32 v9, v66
	v_pk_mul_f32 v[8:9], v[8:9], v[16:17]
	v_and_b32_e32 v19, 0xffff0000, v84
	v_sub_f32_e32 v11, v8, v9
	v_mov_b32_e32 v8, v66
	v_mov_b32_e32 v9, v70
	v_pk_mul_f32 v[8:9], v[8:9], v[16:17]
	v_and_b32_e32 v18, 0xffff0000, v88
	v_add_f32_e32 v8, v9, v8
	v_mov_b32_e32 v66, v71
	v_cndmask_b32_e32 v11, v8, v11, vcc
	v_pk_mul_f32 v[8:9], v[66:67], v[18:19]
	v_mov_b32_e32 v70, v67
	v_sub_f32_e32 v12, v8, v9
	v_pk_mul_f32 v[8:9], v[70:71], v[18:19]
	v_lshlrev_b32_e32 v21, 16, v85
	v_add_f32_e32 v8, v9, v8
	v_lshlrev_b32_e32 v20, 16, v89
	v_cndmask_b32_e32 v12, v8, v12, vcc
	v_mov_b32_e32 v8, v72
	v_mov_b32_e32 v9, v68
	v_pk_mul_f32 v[8:9], v[8:9], v[20:21]
	v_and_b32_e32 v23, 0xffff0000, v85
	v_sub_f32_e32 v13, v8, v9
	v_mov_b32_e32 v8, v68
	v_mov_b32_e32 v9, v72
	v_pk_mul_f32 v[8:9], v[8:9], v[20:21]
	v_and_b32_e32 v22, 0xffff0000, v89
	v_add_f32_e32 v8, v9, v8
	v_mov_b32_e32 v68, v73
	v_cndmask_b32_e32 v13, v8, v13, vcc
	v_pk_mul_f32 v[8:9], v[68:69], v[22:23]
	v_mov_b32_e32 v72, v69
	v_sub_f32_e32 v14, v8, v9
	v_pk_mul_f32 v[8:9], v[72:73], v[22:23]
	s_lshl_b32 s46, s75, 3
	v_add_f32_e32 v8, v9, v8
	s_add_i32 s46, s46, s74
	v_cndmask_b32_e32 v8, v8, v14, vcc
	v_mov_b32_e32 v81, 0
	v_cvt_pk_bf16_f32 v142, v0, v5
	v_cvt_pk_bf16_f32 v143, v7, v10
	v_cvt_pk_bf16_f32 v144, v11, v12
	v_cvt_pk_bf16_f32 v145, v13, v8
	s_cmp_gt_u32 s94, s80
	v_mov_b32_e32 v80, v81
	v_mov_b32_e32 v79, v81
	v_mov_b32_e32 v78, v81
	v_mov_b32_e32 v77, v81
	v_mov_b32_e32 v76, v81
	v_mov_b32_e32 v75, v81
	v_mov_b32_e32 v74, v81
	v_mov_b32_e32 v73, v81
	v_mov_b32_e32 v72, v81
	v_mov_b32_e32 v71, v81
	v_mov_b32_e32 v70, v81
	v_mov_b32_e32 v69, v81
	v_mov_b32_e32 v68, v81
	v_mov_b32_e32 v67, v81
	v_mov_b32_e32 v66, v81
	s_waitcnt vmcnt(6)
	v_mov_b32_e32 v97, v81
	v_mov_b32_e32 v96, v81
	v_mov_b32_e32 v95, v81
	v_mov_b32_e32 v94, v81
	v_mov_b32_e32 v93, v81
	v_mov_b32_e32 v92, v81
	v_mov_b32_e32 v91, v81
	v_mov_b32_e32 v90, v81
	v_mov_b32_e32 v89, v81
	v_mov_b32_e32 v88, v81
	v_mov_b32_e32 v87, v81
	v_mov_b32_e32 v86, v81
	v_mov_b32_e32 v85, v81
	v_mov_b32_e32 v84, v81
	v_mov_b32_e32 v83, v81
	v_mov_b32_e32 v82, v81
	v_mov_b32_e32 v201, v81
	s_cbranch_scc1 .LBB0_410
	v_lshrrev_b32_e32 v5, 3, v6
	v_lshlrev_b32_e32 v166, 4, v6
	v_and_b32_e32 v168, 4, v5
	v_ashrrev_i32_e32 v5, 31, v4
	v_mov_b32_e32 v201, 0
	v_lshlrev_b32_e32 v0, 4, v184
	v_and_b32_e32 v167, 0x3f0, v166
	s_mov_b32 s49, 0
	v_mov_b32_e32 v170, 0xf149f2ca
	v_lshlrev_b64 v[162:163], 1, v[2:3]
	v_lshlrev_b64 v[164:165], 1, v[4:5]
	v_mov_b32_e32 v82, 0
	v_mov_b32_e32 v83, v201
	v_mov_b32_e32 v84, v201
	v_mov_b32_e32 v85, v201
	v_mov_b32_e32 v86, v201
	v_mov_b32_e32 v87, v201
	v_mov_b32_e32 v88, v201
	v_mov_b32_e32 v89, v201
	v_mov_b32_e32 v90, v201
	v_mov_b32_e32 v91, v201
	v_mov_b32_e32 v92, v201
	v_mov_b32_e32 v93, v201
	v_mov_b32_e32 v94, v201
	v_mov_b32_e32 v95, v201
	v_mov_b32_e32 v96, v201
	v_mov_b32_e32 v97, v201
	v_mov_b32_e32 v66, v201
	v_mov_b32_e32 v67, v201
	v_mov_b32_e32 v68, v201
	v_mov_b32_e32 v69, v201
	v_mov_b32_e32 v70, v201
	v_mov_b32_e32 v71, v201
	v_mov_b32_e32 v72, v201
	v_mov_b32_e32 v73, v201
	v_mov_b32_e32 v74, v201
	v_mov_b32_e32 v75, v201
	v_mov_b32_e32 v76, v201
	v_mov_b32_e32 v77, v201
	v_mov_b32_e32 v78, v201
	v_mov_b32_e32 v79, v201
	v_mov_b32_e32 v80, v201
	v_mov_b32_e32 v81, v201
	s_waitcnt vmcnt(0)
	ds_write_b128 v166, v[98:101]
	ds_write_b128 v166, v[102:105] offset:4096
	ds_write_b128 v166, v[106:109] offset:8192
	ds_write_b128 v166, v[110:113] offset:12288
.LBB0_396:
	s_lshl_b32 s52, s49, 14
	s_add_i32 s0, s94, 1
	s_max_i32 s1, s43, s0
	s_mov_b32 s0, s94
	s_waitcnt vmcnt(0)
	s_waitcnt lgkmcnt(0)
	s_barrier
	s_branch .LBB0_398

.LBB0_400:
	s_andn2_b64 vcc, exec, s[12:13]
	s_cbranch_vccz .LBB0_402
	s_ashr_i32 s1, s0, 31
	s_lshl_b64 s[12:13], s[0:1], 13
	s_add_u32 s14, s44, s12
	s_addc_u32 s15, s45, s13
	s_add_u32 s12, s47, s12
	s_addc_u32 s13, s48, s13
	v_readfirstlane_b32 s1, v166
	s_sub_u32 m0, 0x4000, s52
	s_nop 0
	s_add_u32 m0, m0, s1
	s_nop 0
	global_load_lds_dwordx4 v162, s[14:15]
	s_add_u32 m0, m0, 0x1000
	s_nop 0
	global_load_lds_dwordx4 v164, s[14:15]
	s_add_u32 m0, m0, 0x1000
	s_nop 0
	global_load_lds_dwordx4 v162, s[12:13]
	s_add_u32 m0, m0, 0x1000
	s_nop 0
	global_load_lds_dwordx4 v164, s[12:13]
	s_mov_b32 s1, s0

.LBB0_410:
	ds_bpermute_b32 v221, v235, v201
	s_sub_i32 s1, 0x1de1, s77
	s_max_i32 s1, s1, 0
	s_lshl_b32 s0, s86, 19
	s_lshr_b32 s94, s1, 6
	v_mov_b32_e32 v0, v224
	v_mov_b32_e32 v33, 0
	s_cmp_gt_u32 s94, s80
	v_mov_b32_e32 v32, 0
	v_mov_b32_e32 v31, 0
	v_mov_b32_e32 v30, 0
	v_mov_b32_e32 v29, 0
	v_mov_b32_e32 v28, 0
	v_mov_b32_e32 v27, 0
	v_mov_b32_e32 v26, 0
	v_mov_b32_e32 v25, 0
	v_mov_b32_e32 v24, 0
	v_mov_b32_e32 v23, 0
	v_mov_b32_e32 v22, 0
	v_mov_b32_e32 v21, 0
	v_mov_b32_e32 v20, 0
	v_mov_b32_e32 v19, 0
	v_mov_b32_e32 v18, 0
	v_mov_b32_e32 v17, 0
	v_mov_b32_e32 v16, 0
	v_mov_b32_e32 v15, 0
	v_mov_b32_e32 v14, 0
	v_mov_b32_e32 v13, 0
	v_mov_b32_e32 v12, 0
	v_mov_b32_e32 v11, 0
	v_mov_b32_e32 v10, 0
	v_mov_b32_e32 v9, 0
	v_mov_b32_e32 v8, 0
	v_mov_b32_e32 v7, 0
	v_mov_b32_e32 v6, 0
	v_mov_b32_e32 v5, 0
	v_mov_b32_e32 v4, 0
	v_mov_b32_e32 v3, 0
	v_mov_b32_e32 v2, 0
	v_mov_b32_e32 v203, 0
	s_waitcnt lgkmcnt(0)
	s_barrier
	s_cbranch_scc1 .LBB0_235
	s_lshl_b32 s0, s0, 1
	v_readlane_b32 s1, v254, 58
	s_add_u32 s12, s1, s0
	v_readlane_b32 s1, v254, 59
	s_addc_u32 s13, s1, 0
	v_readlane_b32 s1, v254, 60
	v_lshlrev_b32_e32 v2, 3, v0
	s_add_u32 s14, s1, s0
	v_readlane_b32 s0, v254, 61
	v_ashrrev_i32_e32 v3, 31, v2
	s_addc_u32 s15, s0, 0
	s_lshl_b64 s[0:1], s[94:95], 13
	v_lshlrev_b64 v[204:205], 1, v[2:3]
	v_add_u32_e32 v2, 0x800, v2
	s_add_u32 s12, s12, s0
	v_ashrrev_i32_e32 v3, 31, v2
	s_addc_u32 s13, s13, s1
	v_lshlrev_b64 v[206:207], 1, v[2:3]
	v_lshl_add_u64 v[4:5], s[12:13], 0, v[204:205]
	v_lshl_add_u64 v[2:3], s[12:13], 0, v[206:207]
	s_add_u32 s12, s14, s0
	s_addc_u32 s13, s15, s1
	global_load_dwordx4 v[146:149], v[4:5], off
	global_load_dwordx4 v[150:153], v[2:3], off
	v_lshl_add_u64 v[2:3], s[12:13], 0, v[204:205]
	v_lshl_add_u64 v[4:5], s[12:13], 0, v[206:207]
	global_load_dwordx4 v[154:157], v[2:3], off
	global_load_dwordx4 v[158:161], v[4:5], off
	s_add_i32 s12, s46, 0xfffffe07
	s_lshl_b32 s13, s94, 6
	s_add_u32 s0, s42, s0
	v_lshlrev_b32_e32 v238, 4, v0
	v_lshrrev_b32_e32 v0, 3, v0
	s_addc_u32 s1, 0, s1
	v_readlane_b32 s14, v254, 62
	v_mov_b32_e32 v2, v1
	v_mov_b32_e32 v3, v1
	v_mov_b32_e32 v4, v1
	v_mov_b32_e32 v5, v1
	v_mov_b32_e32 v6, v1
	v_mov_b32_e32 v7, v1
	v_mov_b32_e32 v8, v1
	v_mov_b32_e32 v9, v1
	v_mov_b32_e32 v10, v1
	v_mov_b32_e32 v11, v1
	v_mov_b32_e32 v12, v1
	v_mov_b32_e32 v13, v1
	v_mov_b32_e32 v14, v1
	v_mov_b32_e32 v15, v1
	v_mov_b32_e32 v16, v1
	v_mov_b32_e32 v17, v1
	v_mov_b32_e32 v18, v1
	v_mov_b32_e32 v19, v1
	v_mov_b32_e32 v20, v1
	v_mov_b32_e32 v21, v1
	v_mov_b32_e32 v22, v1
	v_mov_b32_e32 v23, v1
	v_mov_b32_e32 v24, v1
	v_mov_b32_e32 v25, v1
	v_mov_b32_e32 v26, v1
	v_mov_b32_e32 v27, v1
	v_mov_b32_e32 v28, v1
	v_mov_b32_e32 v29, v1
	v_mov_b32_e32 v30, v1
	v_mov_b32_e32 v31, v1
	v_and_b32_e32 v240, 4, v0
	v_readlane_b32 s15, v254, 63
	s_add_u32 s0, s14, s0
	v_mov_b32_e32 v0, v1
	v_mov_b64_e32 v[32:33], v[30:31]
	v_and_b32_e32 v239, 0x3f0, v238
	v_add_u32_e32 v241, 0xfffffe00, v200
	s_addc_u32 s1, s15, s1
	s_mov_b32 s14, 0
	v_mov_b32_e32 v203, 0
	v_mov_b32_e32 v242, 0xf149f2ca
	v_mov_b64_e32 v[30:31], v[28:29]
	v_mov_b64_e32 v[28:29], v[26:27]
	v_mov_b64_e32 v[26:27], v[24:25]
	v_mov_b64_e32 v[24:25], v[22:23]
	v_mov_b64_e32 v[22:23], v[20:21]
	v_mov_b64_e32 v[20:21], v[18:19]
	v_mov_b64_e32 v[18:19], v[16:17]
	v_mov_b64_e32 v[16:17], v[14:15]
	v_mov_b64_e32 v[14:15], v[12:13]
	v_mov_b64_e32 v[12:13], v[10:11]
	v_mov_b64_e32 v[10:11], v[8:9]
	v_mov_b64_e32 v[8:9], v[6:7]
	v_mov_b64_e32 v[6:7], v[4:5]
	v_mov_b64_e32 v[4:5], v[2:3]
	v_mov_b64_e32 v[2:3], v[0:1]
	s_waitcnt vmcnt(0)
	ds_write_b128 v238, v[146:149]
	ds_write_b128 v238, v[150:153] offset:4096
	ds_write_b128 v238, v[154:157] offset:8192
	ds_write_b128 v238, v[158:161] offset:12288
.LBB0_412:
	s_lshl_b32 s15, s14, 14
	s_cmp_ge_u32 s94, s80
	s_cselect_b64 s[44:45], -1, 0
	s_and_b64 vcc, exec, s[44:45]
	s_waitcnt vmcnt(0)
	s_waitcnt lgkmcnt(0)
	s_barrier
	s_cbranch_vccnz .LBB0_414
	v_readfirstlane_b32 s40, v238
	s_sub_u32 m0, 0x4000, s15
	s_nop 0
	s_add_u32 m0, m0, s40
	s_add_u32 vcc_lo, s0, 0x13957000
	s_addc_u32 vcc_hi, s1, 0
	global_load_lds_dwordx4 v204, vcc
	s_add_u32 m0, m0, 0x1000
	s_nop 0
	global_load_lds_dwordx4 v206, vcc
	s_add_u32 m0, m0, 0x1000
	s_add_u32 vcc_lo, s0, 0x14957000
	s_addc_u32 vcc_hi, s1, 0
	global_load_lds_dwordx4 v204, vcc
	s_add_u32 m0, m0, 0x1000
	s_nop 0
	global_load_lds_dwordx4 v206, vcc
